# D4: diff loop tile store/load issued piecewise between the PV MFMAs (on G6)
# speedup vs baseline: 1.0988x; 1.0027x over previous
.LBB0_696:
	s_add_i32 s1, s0, 1
	s_cmp_lg_u32 s0, 2
	s_cselect_b32 s9, s1, 0
.LBB0_700:
	s_cmp_gt_i32 s7, s5
	s_waitcnt lgkmcnt(0)
	s_barrier
	s_cbranch_scc1 .Ld4_inactive
	s_mul_i32 s14, s0, 0x4a00
	v_add_u32_e32 v0, s14, v148
	v_add3_u32 v0, v0, v130, v132
	ds_read_b128 v[2:5], v0
	s_waitcnt lgkmcnt(0)
	v_mfma_f32_32x32x16_bf16 v[80:95], v[2:5], v[96:99], v[48:63]
	ds_read_b128 v[2:5], v0 offset:4608
	s_add_i32 s0, s7, 63
	v_cmp_le_i32_e32 vcc, s0, v128
	s_cmp_eq_u64 vcc, exec
	s_waitcnt lgkmcnt(0)
	v_mfma_f32_32x32x16_bf16 v[64:79], v[2:5], v[96:99], v[48:63]
	ds_read_b128 v[2:5], v0 offset:32
	s_waitcnt lgkmcnt(0)
	v_mfma_f32_32x32x16_bf16 v[80:95], v[2:5], v[100:103], v[80:95]
	ds_read_b128 v[2:5], v0 offset:4640
	s_waitcnt lgkmcnt(0)
	v_mfma_f32_32x32x16_bf16 v[64:79], v[2:5], v[100:103], v[64:79]
	s_cbranch_scc1 .LBB0_705
	v_add_u32_e32 v0, s7, v125
	v_cmp_lt_i32_e32 vcc, v0, v128
	v_add_u32_e32 v2, 2, v0
	s_nop 4
	v_cndmask_b32_e32 v81, v169, v81, vcc
	v_cmp_le_i32_e32 vcc, v0, v128
	s_nop 1
	v_cndmask_b32_e32 v80, v169, v80, vcc
	v_cmp_le_i32_e32 vcc, v2, v128
	v_add_u32_e32 v2, 3, v0
	s_nop 0
	v_cndmask_b32_e32 v82, v169, v82, vcc
	v_cmp_le_i32_e32 vcc, v2, v128
	v_add_u32_e32 v2, 8, v0
	s_nop 0
	v_cndmask_b32_e32 v83, v169, v83, vcc
	v_cmp_le_i32_e32 vcc, v2, v128
	v_add_u32_e32 v2, 9, v0
	s_nop 0
	v_cndmask_b32_e32 v84, v169, v84, vcc
	v_cmp_le_i32_e32 vcc, v2, v128
	v_add_u32_e32 v2, 10, v0
	s_nop 0
	v_cndmask_b32_e32 v85, v169, v85, vcc
	v_cmp_le_i32_e32 vcc, v2, v128
	v_add_u32_e32 v2, 11, v0
	s_nop 0
	v_cndmask_b32_e32 v86, v169, v86, vcc
	v_cmp_le_i32_e32 vcc, v2, v128
	v_add_u32_e32 v2, 16, v0
	s_nop 0
	v_cndmask_b32_e32 v87, v169, v87, vcc
	v_cmp_le_i32_e32 vcc, v2, v128
	v_add_u32_e32 v2, 17, v0
	s_nop 0
	v_cndmask_b32_e32 v88, v169, v88, vcc
	v_cmp_le_i32_e32 vcc, v2, v128
	v_add_u32_e32 v2, 18, v0
	s_nop 0
	v_cndmask_b32_e32 v89, v169, v89, vcc
	v_cmp_le_i32_e32 vcc, v2, v128
	v_add_u32_e32 v2, 19, v0
	s_nop 0
	v_cndmask_b32_e32 v90, v169, v90, vcc
	v_cmp_le_i32_e32 vcc, v2, v128
	v_add_u32_e32 v2, 24, v0
	s_nop 0
	v_cndmask_b32_e32 v91, v169, v91, vcc
	v_cmp_le_i32_e32 vcc, v2, v128
	v_add_u32_e32 v2, 25, v0
	s_nop 0
	v_cndmask_b32_e32 v92, v169, v92, vcc
	v_cmp_le_i32_e32 vcc, v2, v128
	v_add_u32_e32 v2, 26, v0
	s_nop 0
	v_cndmask_b32_e32 v93, v169, v93, vcc
	v_cmp_le_i32_e32 vcc, v2, v128
	v_add_u32_e32 v2, 27, v0
	s_nop 0
	v_cndmask_b32_e32 v94, v169, v94, vcc
	v_cmp_le_i32_e32 vcc, v2, v128
	v_add_u32_e32 v2, 32, v0
	s_nop 0
	v_cndmask_b32_e32 v95, v169, v95, vcc
	v_cmp_le_i32_e32 vcc, v2, v128
	v_add_u32_e32 v2, 33, v0
	s_nop 0
	v_cndmask_b32_e32 v64, v169, v64, vcc
	v_cmp_le_i32_e32 vcc, v2, v128
	v_add_u32_e32 v2, 34, v0
	s_nop 0
	v_cndmask_b32_e32 v65, v169, v65, vcc
	v_cmp_le_i32_e32 vcc, v2, v128
	v_add_u32_e32 v2, 35, v0
	s_nop 0
	v_cndmask_b32_e32 v66, v169, v66, vcc
	v_cmp_le_i32_e32 vcc, v2, v128
	v_add_u32_e32 v2, 40, v0
	s_nop 0
	v_cndmask_b32_e32 v67, v169, v67, vcc
	v_cmp_le_i32_e32 vcc, v2, v128
	v_add_u32_e32 v2, 41, v0
	s_nop 0
	v_cndmask_b32_e32 v68, v169, v68, vcc
	v_cmp_le_i32_e32 vcc, v2, v128
	v_add_u32_e32 v2, 42, v0
	s_nop 0
	v_cndmask_b32_e32 v69, v169, v69, vcc
	v_cmp_le_i32_e32 vcc, v2, v128
	v_add_u32_e32 v2, 43, v0
	s_nop 0
	v_cndmask_b32_e32 v70, v169, v70, vcc
	v_cmp_le_i32_e32 vcc, v2, v128
	v_add_u32_e32 v2, 48, v0
	s_nop 0
	v_cndmask_b32_e32 v71, v169, v71, vcc
	v_cmp_le_i32_e32 vcc, v2, v128
	v_add_u32_e32 v2, 49, v0
	s_nop 0
	v_cndmask_b32_e32 v72, v169, v72, vcc
	v_cmp_le_i32_e32 vcc, v2, v128
	v_add_u32_e32 v2, 50, v0
	s_nop 0
	v_cndmask_b32_e32 v73, v169, v73, vcc
	v_cmp_le_i32_e32 vcc, v2, v128
	v_add_u32_e32 v2, 51, v0
	s_nop 0
	v_cndmask_b32_e32 v74, v169, v74, vcc
	v_cmp_le_i32_e32 vcc, v2, v128
	v_add_u32_e32 v2, 56, v0
	s_nop 0
	v_cndmask_b32_e32 v75, v169, v75, vcc
	v_cmp_le_i32_e32 vcc, v2, v128
	v_add_u32_e32 v2, 57, v0
	s_nop 0
	v_cndmask_b32_e32 v76, v169, v76, vcc
	v_cmp_le_i32_e32 vcc, v2, v128
	v_add_u32_e32 v2, 58, v0
	v_add_u32_e32 v0, 59, v0
	v_cndmask_b32_e32 v77, v169, v77, vcc
	v_cmp_le_i32_e32 vcc, v2, v128
	s_nop 1
	v_cndmask_b32_e32 v78, v169, v78, vcc
	v_cmp_gt_i32_e32 vcc, v0, v128
	s_and_saveexec_b64 s[0:1], vcc
	v_mov_b32_e32 v79, 0xf149f2ca
	s_or_b64 exec, exec, s[0:1]
.LBB0_705:
	s_nop 7
	v_exp_f32_e32 v2, v80
	v_exp_f32_e32 v3, v81
	v_exp_f32_e32 v4, v82
	v_exp_f32_e32 v5, v83
	v_add_f32_e32 v0, 0, v2
	v_exp_f32_e32 v6, v84
	v_add_f32_e32 v0, v3, v0
	v_exp_f32_e32 v7, v85
	v_add_f32_e32 v0, v4, v0
	v_exp_f32_e32 v8, v86
	v_add_f32_e32 v0, v5, v0
	v_exp_f32_e32 v9, v87
	v_add_f32_e32 v0, v6, v0
	v_add_f32_e32 v0, v7, v0
	v_add3_u32 v86, s14, v147, v149
	v_add_f32_e32 v0, v8, v0
	v_add_u32_e32 v87, 0x2000, v86
	v_add_f32_e32 v0, v9, v0
	v_cvt_pk_bf16_f32 v2, v2, v3
	v_cvt_pk_bf16_f32 v3, v4, v5
	v_cvt_pk_bf16_f32 v4, v6, v7
	v_cvt_pk_bf16_f32 v5, v8, v9
	ds_read2_b64 v[6:9], v87 offset0:128 offset1:130
	ds_read2_b64 v[10:13], v87 offset0:132 offset1:134
	v_add_u32_e32 v86, 0x3000, v86
	s_waitcnt lgkmcnt(1)
	v_mfma_f32_32x32x16_bf16 v[32:47], v[6:9], v[2:5], v[32:47]
	s_mul_i32 s1, s9, 0x4a00
	v_or_b32_e32 v184, s1, v131
	v_add_u32_e32 v185, v184, v133
	s_waitcnt vmcnt(3)
	ds_write_b128 v185, v[108:111]
	global_load_dwordx4 v[108:111], v180, s[10:11]
	ds_read2_b64 v[6:9], v86 offset0:160 offset1:162
	v_exp_f32_e32 v14, v88
	v_exp_f32_e32 v15, v89
	v_exp_f32_e32 v80, v90
	v_exp_f32_e32 v81, v91
	v_exp_f32_e32 v82, v92
	v_exp_f32_e32 v83, v93
	s_waitcnt lgkmcnt(0)
	v_mfma_f32_32x32x16_bf16 v[16:31], v[6:9], v[2:5], v[16:31]
	ds_read2_b64 v[6:9], v86 offset0:164 offset1:166
	v_exp_f32_e32 v84, v94
	v_exp_f32_e32 v85, v95
	v_cvt_pk_bf16_f32 v2, v14, v15
	v_cvt_pk_bf16_f32 v3, v80, v81
	v_cvt_pk_bf16_f32 v4, v82, v83
	v_cvt_pk_bf16_f32 v5, v84, v85
	v_exp_f32_e32 v64, v64
	v_exp_f32_e32 v65, v65
	s_waitcnt lgkmcnt(0)
	v_mfma_f32_32x32x16_bf16 v[16:31], v[6:9], v[2:5], v[16:31]
	v_add3_u32 v185, v184, v144, s33
	s_waitcnt vmcnt(2)
	ds_write2_b64 v185, v[104:105], v[106:107] offset1:1
	global_load_dwordx4 v[104:107], v182, s[16:17]
	ds_read2_b64 v[6:9], v87 offset0:136 offset1:138
	v_exp_f32_e32 v66, v66
	v_exp_f32_e32 v67, v67
	v_exp_f32_e32 v68, v68
	v_exp_f32_e32 v69, v69
	v_exp_f32_e32 v70, v70
	v_exp_f32_e32 v71, v71
	v_mfma_f32_32x32x16_bf16 v[32:47], v[10:13], v[2:5], v[32:47]
	v_cvt_pk_bf16_f32 v2, v64, v65
	v_cvt_pk_bf16_f32 v3, v66, v67
	v_cvt_pk_bf16_f32 v4, v68, v69
	v_cvt_pk_bf16_f32 v5, v70, v71
	v_add_f32_e32 v0, v14, v0
	v_add_f32_e32 v0, v15, v0
	v_add_f32_e32 v0, v80, v0
	s_waitcnt lgkmcnt(0)
	v_mfma_f32_32x32x16_bf16 v[32:47], v[6:9], v[2:5], v[32:47]
	v_add_u32_e32 v185, v184, v145
	s_waitcnt vmcnt(3)
	ds_write_b128 v185, v[112:115]
	global_load_dwordx4 v[112:115], v181, s[10:11]
	ds_read2_b64 v[6:9], v86 offset0:168 offset1:170
	v_add_f32_e32 v0, v81, v0
	v_exp_f32_e32 v72, v72
	v_exp_f32_e32 v73, v73
	v_exp_f32_e32 v74, v74
	v_exp_f32_e32 v75, v75
	v_exp_f32_e32 v76, v76
	s_waitcnt lgkmcnt(0)
	v_mfma_f32_32x32x16_bf16 v[16:31], v[6:9], v[2:5], v[16:31]
	ds_read2_b64 v[6:9], v87 offset0:140 offset1:142
	v_exp_f32_e32 v77, v77
	v_exp_f32_e32 v78, v78
	v_exp_f32_e32 v79, v79
	v_add_f32_e32 v0, v82, v0
	v_add_f32_e32 v0, v83, v0
	v_add_f32_e32 v0, v84, v0
	v_add_f32_e32 v0, v85, v0
	v_cvt_pk_bf16_f32 v2, v72, v73
	v_cvt_pk_bf16_f32 v3, v74, v75
	v_cvt_pk_bf16_f32 v4, v76, v77
	v_cvt_pk_bf16_f32 v5, v78, v79
	v_add_f32_e32 v0, v64, v0
	v_add_f32_e32 v0, v65, v0
	s_waitcnt lgkmcnt(0)
	v_mfma_f32_32x32x16_bf16 v[32:47], v[6:9], v[2:5], v[32:47]
	v_add3_u32 v185, v184, v146, s33
	s_waitcnt vmcnt(3)
	ds_write2_b64 v185, v[116:117], v[118:119] offset1:1
	global_load_dwordx4 v[116:119], v183, s[16:17]
	s_add_u32 s10, s10, 0x2000
	s_addc_u32 s11, s11, 0
	s_add_u32 s16, s16, 0x80
	s_addc_u32 s17, s17, 0
	ds_read2_b64 v[6:9], v86 offset0:172 offset1:174
	v_add_f32_e32 v0, v66, v0
	v_add_f32_e32 v0, v67, v0
	v_add_f32_e32 v0, v68, v0
	v_add_f32_e32 v0, v69, v0
	v_add_f32_e32 v0, v70, v0
	v_add_f32_e32 v0, v71, v0
	v_add_f32_e32 v0, v72, v0
	v_add_f32_e32 v0, v73, v0
	s_waitcnt lgkmcnt(0)
	v_mfma_f32_32x32x16_bf16 v[16:31], v[6:9], v[2:5], v[16:31]
	v_add_f32_e32 v0, v74, v0
	v_add_f32_e32 v0, v75, v0
	v_add_f32_e32 v0, v76, v0
	v_add_f32_e32 v0, v77, v0
	v_add_f32_e32 v0, v78, v0
	v_add_f32_e32 v0, v79, v0
	v_add_f32_e32 v152, v152, v0
	v_cmp_lt_f32_e32 vcc, s20, v0
	s_cbranch_vccz .LBB0_707
	v_mov_b32_e32 v2, v0
	s_nop 1
	v_permlane32_swap_b32_e32 v0, v2
	v_add_f32_e32 v0, v0, v2
	v_log_f32_e32 v2, v0
	v_cmp_lt_f32_e32 vcc, s20, v0
	s_nop 1
	v_cndmask_b32_e32 v2, 0, v2, vcc
	v_exp_f32_e64 v0, -v2
	v_add_f32_e32 v153, v153, v2
	v_xor_b32_e32 v63, 0x80000000, v153
	v_mov_b32_e32 v62, v63
	v_mul_f32_e32 v152, v152, v0
	v_pk_mul_f32 v[46:47], v[46:47], v[0:1] op_sel_hi:[1,0]
	v_pk_mul_f32 v[44:45], v[44:45], v[0:1] op_sel_hi:[1,0]
	v_pk_mul_f32 v[42:43], v[42:43], v[0:1] op_sel_hi:[1,0]
	v_pk_mul_f32 v[40:41], v[40:41], v[0:1] op_sel_hi:[1,0]
	v_pk_mul_f32 v[38:39], v[38:39], v[0:1] op_sel_hi:[1,0]
	v_pk_mul_f32 v[36:37], v[36:37], v[0:1] op_sel_hi:[1,0]
	v_pk_mul_f32 v[34:35], v[34:35], v[0:1] op_sel_hi:[1,0]
	v_pk_mul_f32 v[32:33], v[32:33], v[0:1] op_sel_hi:[1,0]
	v_pk_mul_f32 v[30:31], v[30:31], v[0:1] op_sel_hi:[1,0]
	v_pk_mul_f32 v[28:29], v[28:29], v[0:1] op_sel_hi:[1,0]
	v_pk_mul_f32 v[26:27], v[26:27], v[0:1] op_sel_hi:[1,0]
	v_pk_mul_f32 v[24:25], v[24:25], v[0:1] op_sel_hi:[1,0]
	v_pk_mul_f32 v[22:23], v[22:23], v[0:1] op_sel_hi:[1,0]
	v_pk_mul_f32 v[20:21], v[20:21], v[0:1] op_sel_hi:[1,0]
	v_pk_mul_f32 v[18:19], v[18:19], v[0:1] op_sel_hi:[1,0]
	v_pk_mul_f32 v[16:17], v[16:17], v[0:1] op_sel_hi:[1,0]
	v_mov_b32_e32 v61, v63
	v_mov_b32_e32 v60, v63
	v_mov_b32_e32 v59, v63
	v_mov_b32_e32 v58, v63
	v_mov_b32_e32 v57, v63
	v_mov_b32_e32 v56, v63
	v_mov_b32_e32 v55, v63
	v_mov_b32_e32 v54, v63
	v_mov_b32_e32 v53, v63
	v_mov_b32_e32 v52, v63
	v_mov_b32_e32 v51, v63
	v_mov_b32_e32 v50, v63
	v_mov_b32_e32 v49, v63
	v_mov_b32_e32 v48, v63
	s_branch .LBB0_707
.Ld4_inactive:
	s_mul_i32 s1, s9, 0x4a00
	v_or_b32_e32 v184, s1, v131
	v_add_u32_e32 v185, v184, v133
	s_waitcnt vmcnt(3)
	ds_write_b128 v185, v[108:111]
	global_load_dwordx4 v[108:111], v180, s[10:11]
	v_add3_u32 v185, v184, v144, s33
	s_waitcnt vmcnt(2)
	ds_write2_b64 v185, v[104:105], v[106:107] offset1:1
	global_load_dwordx4 v[104:107], v182, s[16:17]
	v_add_u32_e32 v185, v184, v145
	s_waitcnt vmcnt(3)
	ds_write_b128 v185, v[112:115]
	global_load_dwordx4 v[112:115], v181, s[10:11]
	v_add3_u32 v185, v184, v146, s33
	s_waitcnt vmcnt(3)
	ds_write2_b64 v185, v[116:117], v[118:119] offset1:1
	global_load_dwordx4 v[116:119], v183, s[16:17]
	s_add_u32 s10, s10, 0x2000
	s_addc_u32 s11, s11, 0
	s_add_u32 s16, s16, 0x80
	s_addc_u32 s17, s17, 0

.LBB0_720:
	v_lshl_add_u64 v[82:83], s[80:81], 0, v[66:67]
	v_lshl_add_u64 v[84:85], v[82:83], 0, s[34:35]
	s_add_i32 m0, s7, 0x8000
	s_nop 0
	global_load_lds_dwordx4 v[84:85], off
	v_lshl_add_u64 v[84:85], s[80:81], 0, v[68:69]
	v_lshl_add_u64 v[86:87], v[84:85], 0, s[42:43]
	s_add_i32 m0, s7, 0xc000
	s_nop 0
	global_load_lds_dwordx4 v[86:87], off
	v_lshl_add_u64 v[86:87], s[80:81], 0, v[70:71]
	v_lshl_add_u64 v[88:89], v[86:87], 0, s[34:35]
	s_add_i32 m0, s7, 0x8400
	s_nop 0
	global_load_lds_dwordx4 v[88:89], off
	v_lshl_add_u64 v[88:89], s[80:81], 0, v[72:73]
	v_lshl_add_u64 v[90:91], v[88:89], 0, s[42:43]
	s_add_i32 m0, s7, 0xc400
	s_nop 0
	global_load_lds_dwordx4 v[90:91], off
	v_lshl_add_u64 v[90:91], s[80:81], 0, v[74:75]
	v_lshl_add_u64 v[92:93], v[90:91], 0, s[34:35]
	s_add_i32 m0, s7, 0x8800
	s_nop 0
	global_load_lds_dwordx4 v[92:93], off
	v_lshl_add_u64 v[92:93], s[80:81], 0, v[76:77]
	v_lshl_add_u64 v[94:95], v[92:93], 0, s[42:43]
	s_add_i32 m0, s7, 0xc800
	s_nop 0
	global_load_lds_dwordx4 v[94:95], off
	v_lshl_add_u64 v[94:95], s[80:81], 0, v[78:79]
	v_lshl_add_u64 v[96:97], v[94:95], 0, s[34:35]
	s_add_i32 m0, s7, 0x8c00
	s_nop 0
	global_load_lds_dwordx4 v[96:97], off
	v_lshl_add_u64 v[96:97], s[80:81], 0, v[80:81]
	v_lshl_add_u64 v[108:109], v[96:97], 0, s[42:43]
	s_add_i32 m0, s7, 0xcc00
	s_cmp_gt_u32 s15, 29
	global_load_lds_dwordx4 v[108:109], off
	s_waitcnt lgkmcnt(0)
	ds_read_b128 v[108:111], v99 offset:0
	ds_read_b128 v[116:119], v100 offset:0
	ds_read_b128 v[112:115], v99 offset:4096
	ds_read_b128 v[128:131], v100 offset:4096
	ds_read_b128 v[132:135], v101 offset:0
	ds_read_b128 v[140:143], v102 offset:0
	ds_read_b128 v[136:139], v101 offset:4096
	ds_read_b128 v[144:147], v102 offset:4096
	s_waitcnt lgkmcnt(4)
	v_mfma_f32_32x32x16_bf16 v[50:65], v[108:111], v[116:119], v[50:65]
	v_mfma_f32_32x32x16_bf16 v[34:49], v[108:111], v[128:131], v[34:49]
	v_mfma_f32_32x32x16_bf16 v[18:33], v[112:115], v[116:119], v[18:33]
	v_mfma_f32_32x32x16_bf16 v[2:17], v[112:115], v[128:131], v[2:17]
	ds_read_b128 v[148:151], v103 offset:0
	ds_read_b128 v[180:183], v104 offset:0
	ds_read_b128 v[152:155], v103 offset:4096
	ds_read_b128 v[184:187], v104 offset:4096
	s_waitcnt lgkmcnt(4)
	v_mfma_f32_32x32x16_bf16 v[50:65], v[132:135], v[140:143], v[50:65]
	v_mfma_f32_32x32x16_bf16 v[34:49], v[132:135], v[144:147], v[34:49]
	v_mfma_f32_32x32x16_bf16 v[18:33], v[136:139], v[140:143], v[18:33]
	v_mfma_f32_32x32x16_bf16 v[2:17], v[136:139], v[144:147], v[2:17]
	ds_read_b128 v[108:111], v105 offset:0
	ds_read_b128 v[116:119], v106 offset:0
	ds_read_b128 v[112:115], v105 offset:4096
	ds_read_b128 v[128:131], v106 offset:4096
	s_waitcnt lgkmcnt(4)
	v_mfma_f32_32x32x16_bf16 v[50:65], v[148:151], v[180:183], v[50:65]
	v_mfma_f32_32x32x16_bf16 v[34:49], v[148:151], v[184:187], v[34:49]
	v_mfma_f32_32x32x16_bf16 v[18:33], v[152:155], v[180:183], v[18:33]
	v_mfma_f32_32x32x16_bf16 v[2:17], v[152:155], v[184:187], v[2:17]
	s_waitcnt lgkmcnt(0)
	v_mfma_f32_32x32x16_bf16 v[50:65], v[108:111], v[116:119], v[50:65]
	v_mfma_f32_32x32x16_bf16 v[34:49], v[108:111], v[128:131], v[34:49]
	v_mfma_f32_32x32x16_bf16 v[18:33], v[112:115], v[116:119], v[18:33]
	v_mfma_f32_32x32x16_bf16 v[2:17], v[112:115], v[128:131], v[2:17]

	s_waitcnt vmcnt(0)
	s_cselect_b64 s[8:9], -1, 0
	s_and_b64 vcc, exec, s[8:9]
	s_waitcnt vmcnt(0) lgkmcnt(0)
	s_barrier
	s_cbranch_vccnz .LBB0_719
	s_mov_b32 m0, s7
	v_lshl_add_u64 v[82:83], v[82:83], 0, s[36:37]
	global_load_lds_dwordx4 v[82:83], off
	v_lshl_add_u64 v[82:83], v[84:85], 0, s[46:47]
	s_mov_b32 m0, s16
	s_nop 0
	global_load_lds_dwordx4 v[82:83], off
	v_lshl_add_u64 v[82:83], v[86:87], 0, s[36:37]
	s_add_i32 m0, s7, 0x400
	s_nop 0
	global_load_lds_dwordx4 v[82:83], off
	v_lshl_add_u64 v[82:83], v[88:89], 0, s[46:47]
	s_mov_b32 m0, s17
	s_nop 0
	global_load_lds_dwordx4 v[82:83], off
	v_lshl_add_u64 v[82:83], v[90:91], 0, s[36:37]
	s_add_i32 m0, s7, 0x800
	s_nop 0
	global_load_lds_dwordx4 v[82:83], off
	v_lshl_add_u64 v[82:83], v[92:93], 0, s[46:47]
	s_mov_b32 m0, s22
	s_nop 0
	global_load_lds_dwordx4 v[82:83], off
	v_lshl_add_u64 v[82:83], v[94:95], 0, s[36:37]
	s_add_i32 m0, s7, 0xc00
	s_nop 0
	global_load_lds_dwordx4 v[82:83], off
	v_lshl_add_u64 v[82:83], v[96:97], 0, s[46:47]
	s_mov_b32 m0, s23
	s_nop 0
	global_load_lds_dwordx4 v[82:83], off
	s_branch .LBB0_719
.Ld4_exit:
	s_waitcnt vmcnt(0)
.LBB0_722:
	v_mov_b32_e32 v0, v152
	s_nop 1
	v_permlane32_swap_b32_e32 v152, v0
	v_add_f32_e32 v0, v152, v0
	v_div_scale_f32 v2, s[0:1], v0, v0, 1.0
	v_rcp_f32_e32 v3, v2
	v_cmp_ne_u32_e64 s[0:1], 0, v143
	s_barrier
	v_fma_f32 v4, -v2, v3, 1.0
	v_fmac_f32_e32 v3, v4, v3
	v_div_scale_f32 v4, vcc, 1.0, v0, 1.0
	v_mul_f32_e32 v5, v4, v3
	v_fma_f32 v6, -v2, v5, v4
	v_fmac_f32_e32 v5, v6, v3
	v_fma_f32 v2, -v2, v5, v4
	v_div_fmas_f32 v2, v2, v3, v5
	v_div_fixup_f32 v2, v2, v0, 1.0
	v_cmp_lt_f32_e32 vcc, 0, v0
	v_lshlrev_b32_e32 v0, 2, v141
	v_lshlrev_b32_e32 v3, 9, v140
	v_cndmask_b32_e32 v14, 0, v2, vcc
	v_lshlrev_b32_e32 v2, 13, v142
	v_cmp_eq_u32_e32 vcc, 0, v143
	v_or3_b32 v0, v0, v2, v3
	s_and_saveexec_b64 s[4:5], s[0:1]
	s_cbranch_execz .LBB0_724
	v_mul_f32_e32 v2, v32, v14
	v_mul_f32_e32 v3, v33, v14
	v_add_u32_e32 v4, 0xdc00, v0
	ds_write2_b32 v4, v2, v3 offset0:128 offset1:160
	v_mul_f32_e32 v2, v34, v14
	v_mul_f32_e32 v3, v35, v14
	ds_write2_b32 v4, v2, v3 offset0:192 offset1:224
	v_mul_f32_e32 v2, v36, v14
	v_mul_f32_e32 v3, v37, v14
	v_add_u32_e32 v4, 0xe000, v0
	ds_write2_b32 v4, v2, v3 offset0:128 offset1:160
	v_mul_f32_e32 v2, v38, v14
	v_mul_f32_e32 v3, v39, v14
	ds_write2_b32 v4, v2, v3 offset0:192 offset1:224
	v_mul_f32_e32 v2, v40, v14
	v_mul_f32_e32 v3, v41, v14
	v_add_u32_e32 v4, 0xe400, v0
	ds_write2_b32 v4, v2, v3 offset0:128 offset1:160
	v_mul_f32_e32 v2, v42, v14
	v_mul_f32_e32 v3, v43, v14
	ds_write2_b32 v4, v2, v3 offset0:192 offset1:224
	v_mul_f32_e32 v2, v44, v14
	v_mul_f32_e32 v3, v45, v14
	v_add_u32_e32 v4, 0xe800, v0
	ds_write2_b32 v4, v2, v3 offset0:128 offset1:160
	v_mul_f32_e32 v2, v46, v14
	v_mul_f32_e32 v3, v47, v14
	ds_write2_b32 v4, v2, v3 offset0:192 offset1:224
	v_mul_f32_e32 v2, v16, v14
	v_mul_f32_e32 v3, v17, v14
	v_add_u32_e32 v4, 0xec00, v0
	ds_write2_b32 v4, v2, v3 offset0:128 offset1:160
	v_mul_f32_e32 v2, v18, v14
	v_mul_f32_e32 v3, v19, v14
	ds_write2_b32 v4, v2, v3 offset0:192 offset1:224
	v_mul_f32_e32 v2, v20, v14
	v_mul_f32_e32 v3, v21, v14
	v_add_u32_e32 v4, 0xf000, v0
	ds_write2_b32 v4, v2, v3 offset0:128 offset1:160
	v_mul_f32_e32 v2, v22, v14
	v_mul_f32_e32 v3, v23, v14
	ds_write2_b32 v4, v2, v3 offset0:192 offset1:224
	v_mul_f32_e32 v2, v24, v14
	v_mul_f32_e32 v3, v25, v14
	v_add_u32_e32 v4, 0xf400, v0
	ds_write2_b32 v4, v2, v3 offset0:128 offset1:160
	v_mul_f32_e32 v2, v26, v14
	v_mul_f32_e32 v3, v27, v14
	ds_write2_b32 v4, v2, v3 offset0:192 offset1:224
	v_mul_f32_e32 v2, v28, v14
	v_mul_f32_e32 v3, v29, v14
	v_add_u32_e32 v4, 0xf800, v0
	ds_write2_b32 v4, v2, v3 offset0:128 offset1:160
	v_mul_f32_e32 v2, v30, v14
	v_mul_f32_e32 v3, v31, v14
	ds_write2_b32 v4, v2, v3 offset0:192 offset1:224
